# phase 9 f32 MFMA product with four interleaved accumulators (k mod 4) so no MFMA waits on the previous one
# baseline (speedup 1.0000x reference)
.LBB0_1169:
	s_andn2_saveexec_b64 s[12:13], s[12:13]
	v_mul_f32_e32 v36, v35, v35
	v_mov_b32_e32 v37, 0x3ca908c9
	v_fmac_f32_e32 v37, 0xbbbac73d, v36
	v_fmaak_f32 v37, v36, v37, 0xbd5c1c4e
	v_fmaak_f32 v37, v36, v37, 0x3e088382
	v_fmaak_f32 v37, v36, v37, 0xbeaaaa99
	v_mul_f32_e64 v37, |v35|, v37
	v_fma_f32 v36, v36, v37, |v35|
	s_or_b64 exec, exec, s[12:13]
	s_brev_b32 s4, -2
	v_bfi_b32 v35, s4, v36, v35
	v_mul_f32_e32 v34, 0.5, v34
	v_add_f32_e32 v35, 1.0, v35
	v_mul_f32_e32 v34, v34, v35
	v_lshlrev_b32_e32 v36, 5, v1
	ds_write_b32 v39, v34 offset:3840
	v_lshlrev_b32_e32 v34, 4, v1
	v_and_b32_e32 v36, 0xffffc000, v36
	v_and_b32_e32 v35, 0xf0, v34
	v_add_u32_e32 v36, 0, v36
	v_and_b32_e32 v34, 0x1f00, v34
	v_add3_u32 v34, v36, v34, v35
	ds_write_b128 v34, v[2:5] offset:8192
	ds_write_b128 v34, v[6:9] offset:24576
	ds_write_b128 v34, v[10:13] offset:40960
	ds_write_b128 v34, v[14:17] offset:57344
	v_add_u32_e32 v2, 0x12000, v34
	ds_write_b128 v2, v[18:21]
	v_add_u32_e32 v2, 0x16000, v34
	ds_write_b128 v2, v[22:25]
	v_add_u32_e32 v2, 0x1a000, v34
	ds_write_b128 v2, v[26:29]
	v_add_u32_e32 v2, 0x1e000, v34
	ds_write_b128 v2, v[30:33]
	s_waitcnt lgkmcnt(0)
	s_barrier
	v_lshlrev_b32_e32 v40, 2, v106
	v_add_u32_e32 v2, 0, v40
	v_mov_b32_e32 v4, 0
	s_and_b32 s16, s23, 0xffc
	s_mov_b32 s12, 0
	v_add_u32_e32 v39, 0x2000, v2
	v_mov_b32_e32 v5, v4
	v_mov_b32_e32 v2, v4
	v_mov_b32_e32 v3, v4
	v_and_b32_e32 v78, 3, v106
	v_lshlrev_b32_e32 v78, 10, v78
	v_add_u32_e32 v78, s11, v78
	v_mov_b32_e32 v79, v39
	v_mov_b32_e32 v174, 0
	v_mov_b32_e32 v175, 0
	v_mov_b32_e32 v176, 0
	v_mov_b32_e32 v177, 0
	v_mov_b32_e32 v178, 0
	v_mov_b32_e32 v179, 0
	v_mov_b32_e32 v180, 0
	v_mov_b32_e32 v181, 0
	v_mov_b32_e32 v182, 0
	v_mov_b32_e32 v183, 0
	v_mov_b32_e32 v184, 0
	v_mov_b32_e32 v185, 0
	v_mov_b32_e32 v186, 0
	v_mov_b32_e32 v187, 0
	v_mov_b32_e32 v188, 0
	v_mov_b32_e32 v189, 0
	ds_read_b128 v[6:9], v78
	ds_read_b128 v[10:13], v78 offset:16
	ds_read_b128 v[14:17], v78 offset:32
	ds_read_b128 v[18:21], v78 offset:48
	ds_read_b128 v[22:25], v78 offset:64
	ds_read_b128 v[26:29], v78 offset:80
	ds_read_b128 v[30:33], v78 offset:96
	ds_read_b128 v[34:37], v78 offset:112
	ds_read2st64_b32 v[42:43], v79 offset1:1
	ds_read2st64_b32 v[44:45], v79 offset0:2 offset1:3
	ds_read2st64_b32 v[46:47], v79 offset0:4 offset1:5
	ds_read2st64_b32 v[48:49], v79 offset0:6 offset1:7
	ds_read2st64_b32 v[50:51], v79 offset0:8 offset1:9
	ds_read2st64_b32 v[52:53], v79 offset0:10 offset1:11
	ds_read2st64_b32 v[54:55], v79 offset0:12 offset1:13
	ds_read2st64_b32 v[56:57], v79 offset0:14 offset1:15
	ds_read2st64_b32 v[58:59], v79 offset0:16 offset1:17
	ds_read2st64_b32 v[60:61], v79 offset0:18 offset1:19
	ds_read2st64_b32 v[62:63], v79 offset0:20 offset1:21
	ds_read2st64_b32 v[64:65], v79 offset0:22 offset1:23
	ds_read2st64_b32 v[66:67], v79 offset0:24 offset1:25
	ds_read2st64_b32 v[68:69], v79 offset0:26 offset1:27
	ds_read2st64_b32 v[70:71], v79 offset0:28 offset1:29
	ds_read2st64_b32 v[72:73], v79 offset0:30 offset1:31
	s_waitcnt lgkmcnt(0)
	v_add_u32_e32 v79, 0x4000, v79
	ds_read_b128 v[110:113], v78 offset:128
	ds_read_b128 v[114:117], v78 offset:144
	ds_read_b128 v[118:121], v78 offset:160
	ds_read_b128 v[122:125], v78 offset:176
	ds_read_b128 v[126:129], v78 offset:192
	ds_read_b128 v[130:133], v78 offset:208
	ds_read_b128 v[134:137], v78 offset:224
	ds_read_b128 v[138:141], v78 offset:240
	ds_read2st64_b32 v[142:143], v79 offset1:1
	ds_read2st64_b32 v[144:145], v79 offset0:2 offset1:3
	ds_read2st64_b32 v[146:147], v79 offset0:4 offset1:5
	ds_read2st64_b32 v[148:149], v79 offset0:6 offset1:7
	ds_read2st64_b32 v[150:151], v79 offset0:8 offset1:9
	ds_read2st64_b32 v[152:153], v79 offset0:10 offset1:11
	ds_read2st64_b32 v[154:155], v79 offset0:12 offset1:13
	ds_read2st64_b32 v[156:157], v79 offset0:14 offset1:15
	ds_read2st64_b32 v[158:159], v79 offset0:16 offset1:17
	ds_read2st64_b32 v[160:161], v79 offset0:18 offset1:19
	ds_read2st64_b32 v[162:163], v79 offset0:20 offset1:21
	ds_read2st64_b32 v[164:165], v79 offset0:22 offset1:23
	ds_read2st64_b32 v[166:167], v79 offset0:24 offset1:25
	ds_read2st64_b32 v[168:169], v79 offset0:26 offset1:27
	ds_read2st64_b32 v[170:171], v79 offset0:28 offset1:29
	ds_read2st64_b32 v[172:173], v79 offset0:30 offset1:31
	v_mfma_f32_4x4x1_16b_f32 v[174:177], v6, v42, v[174:177]
	v_mfma_f32_4x4x1_16b_f32 v[178:181], v7, v43, v[178:181]
	v_mfma_f32_4x4x1_16b_f32 v[182:185], v8, v44, v[182:185]
	v_mfma_f32_4x4x1_16b_f32 v[186:189], v9, v45, v[186:189]
	v_mfma_f32_4x4x1_16b_f32 v[174:177], v10, v46, v[174:177]
	v_mfma_f32_4x4x1_16b_f32 v[178:181], v11, v47, v[178:181]
	v_mfma_f32_4x4x1_16b_f32 v[182:185], v12, v48, v[182:185]
	v_mfma_f32_4x4x1_16b_f32 v[186:189], v13, v49, v[186:189]
	v_mfma_f32_4x4x1_16b_f32 v[174:177], v14, v50, v[174:177]
	v_mfma_f32_4x4x1_16b_f32 v[178:181], v15, v51, v[178:181]
	v_mfma_f32_4x4x1_16b_f32 v[182:185], v16, v52, v[182:185]
	v_mfma_f32_4x4x1_16b_f32 v[186:189], v17, v53, v[186:189]
	v_mfma_f32_4x4x1_16b_f32 v[174:177], v18, v54, v[174:177]
	v_mfma_f32_4x4x1_16b_f32 v[178:181], v19, v55, v[178:181]
	v_mfma_f32_4x4x1_16b_f32 v[182:185], v20, v56, v[182:185]
	v_mfma_f32_4x4x1_16b_f32 v[186:189], v21, v57, v[186:189]
	v_mfma_f32_4x4x1_16b_f32 v[174:177], v22, v58, v[174:177]
	v_mfma_f32_4x4x1_16b_f32 v[178:181], v23, v59, v[178:181]
	v_mfma_f32_4x4x1_16b_f32 v[182:185], v24, v60, v[182:185]
	v_mfma_f32_4x4x1_16b_f32 v[186:189], v25, v61, v[186:189]
	v_mfma_f32_4x4x1_16b_f32 v[174:177], v26, v62, v[174:177]
	v_mfma_f32_4x4x1_16b_f32 v[178:181], v27, v63, v[178:181]
	v_mfma_f32_4x4x1_16b_f32 v[182:185], v28, v64, v[182:185]
	v_mfma_f32_4x4x1_16b_f32 v[186:189], v29, v65, v[186:189]
	v_mfma_f32_4x4x1_16b_f32 v[174:177], v30, v66, v[174:177]
	v_mfma_f32_4x4x1_16b_f32 v[178:181], v31, v67, v[178:181]
	v_mfma_f32_4x4x1_16b_f32 v[182:185], v32, v68, v[182:185]
	v_mfma_f32_4x4x1_16b_f32 v[186:189], v33, v69, v[186:189]
	v_mfma_f32_4x4x1_16b_f32 v[174:177], v34, v70, v[174:177]
	v_mfma_f32_4x4x1_16b_f32 v[178:181], v35, v71, v[178:181]
	v_mfma_f32_4x4x1_16b_f32 v[182:185], v36, v72, v[182:185]
	v_mfma_f32_4x4x1_16b_f32 v[186:189], v37, v73, v[186:189]
	s_waitcnt lgkmcnt(0)
	v_add_u32_e32 v79, 0x4000, v79
	ds_read_b128 v[6:9], v78 offset:256
	ds_read_b128 v[10:13], v78 offset:272
	ds_read_b128 v[14:17], v78 offset:288
	ds_read_b128 v[18:21], v78 offset:304
	ds_read_b128 v[22:25], v78 offset:320
	ds_read_b128 v[26:29], v78 offset:336
	ds_read_b128 v[30:33], v78 offset:352
	ds_read_b128 v[34:37], v78 offset:368
	ds_read2st64_b32 v[42:43], v79 offset1:1
	ds_read2st64_b32 v[44:45], v79 offset0:2 offset1:3
	ds_read2st64_b32 v[46:47], v79 offset0:4 offset1:5
	ds_read2st64_b32 v[48:49], v79 offset0:6 offset1:7
	ds_read2st64_b32 v[50:51], v79 offset0:8 offset1:9
	ds_read2st64_b32 v[52:53], v79 offset0:10 offset1:11
	ds_read2st64_b32 v[54:55], v79 offset0:12 offset1:13
	ds_read2st64_b32 v[56:57], v79 offset0:14 offset1:15
	ds_read2st64_b32 v[58:59], v79 offset0:16 offset1:17
	ds_read2st64_b32 v[60:61], v79 offset0:18 offset1:19
	ds_read2st64_b32 v[62:63], v79 offset0:20 offset1:21
	ds_read2st64_b32 v[64:65], v79 offset0:22 offset1:23
	ds_read2st64_b32 v[66:67], v79 offset0:24 offset1:25
	ds_read2st64_b32 v[68:69], v79 offset0:26 offset1:27
	ds_read2st64_b32 v[70:71], v79 offset0:28 offset1:29
	ds_read2st64_b32 v[72:73], v79 offset0:30 offset1:31
	v_mfma_f32_4x4x1_16b_f32 v[174:177], v110, v142, v[174:177]
	v_mfma_f32_4x4x1_16b_f32 v[178:181], v111, v143, v[178:181]
	v_mfma_f32_4x4x1_16b_f32 v[182:185], v112, v144, v[182:185]
	v_mfma_f32_4x4x1_16b_f32 v[186:189], v113, v145, v[186:189]
	v_mfma_f32_4x4x1_16b_f32 v[174:177], v114, v146, v[174:177]
	v_mfma_f32_4x4x1_16b_f32 v[178:181], v115, v147, v[178:181]
	v_mfma_f32_4x4x1_16b_f32 v[182:185], v116, v148, v[182:185]
	v_mfma_f32_4x4x1_16b_f32 v[186:189], v117, v149, v[186:189]
	v_mfma_f32_4x4x1_16b_f32 v[174:177], v118, v150, v[174:177]
	v_mfma_f32_4x4x1_16b_f32 v[178:181], v119, v151, v[178:181]
	v_mfma_f32_4x4x1_16b_f32 v[182:185], v120, v152, v[182:185]
	v_mfma_f32_4x4x1_16b_f32 v[186:189], v121, v153, v[186:189]
	v_mfma_f32_4x4x1_16b_f32 v[174:177], v122, v154, v[174:177]
	v_mfma_f32_4x4x1_16b_f32 v[178:181], v123, v155, v[178:181]
	v_mfma_f32_4x4x1_16b_f32 v[182:185], v124, v156, v[182:185]
	v_mfma_f32_4x4x1_16b_f32 v[186:189], v125, v157, v[186:189]
	v_mfma_f32_4x4x1_16b_f32 v[174:177], v126, v158, v[174:177]
	v_mfma_f32_4x4x1_16b_f32 v[178:181], v127, v159, v[178:181]
	v_mfma_f32_4x4x1_16b_f32 v[182:185], v128, v160, v[182:185]
	v_mfma_f32_4x4x1_16b_f32 v[186:189], v129, v161, v[186:189]
	v_mfma_f32_4x4x1_16b_f32 v[174:177], v130, v162, v[174:177]
	v_mfma_f32_4x4x1_16b_f32 v[178:181], v131, v163, v[178:181]
	v_mfma_f32_4x4x1_16b_f32 v[182:185], v132, v164, v[182:185]
	v_mfma_f32_4x4x1_16b_f32 v[186:189], v133, v165, v[186:189]
	v_mfma_f32_4x4x1_16b_f32 v[174:177], v134, v166, v[174:177]
	v_mfma_f32_4x4x1_16b_f32 v[178:181], v135, v167, v[178:181]
	v_mfma_f32_4x4x1_16b_f32 v[182:185], v136, v168, v[182:185]
	v_mfma_f32_4x4x1_16b_f32 v[186:189], v137, v169, v[186:189]
	v_mfma_f32_4x4x1_16b_f32 v[174:177], v138, v170, v[174:177]
	v_mfma_f32_4x4x1_16b_f32 v[178:181], v139, v171, v[178:181]
	v_mfma_f32_4x4x1_16b_f32 v[182:185], v140, v172, v[182:185]
	v_mfma_f32_4x4x1_16b_f32 v[186:189], v141, v173, v[186:189]
	s_waitcnt lgkmcnt(0)
	v_add_u32_e32 v79, 0x4000, v79
	ds_read_b128 v[110:113], v78 offset:384
	ds_read_b128 v[114:117], v78 offset:400
	ds_read_b128 v[118:121], v78 offset:416
	ds_read_b128 v[122:125], v78 offset:432
	ds_read_b128 v[126:129], v78 offset:448
	ds_read_b128 v[130:133], v78 offset:464
	ds_read_b128 v[134:137], v78 offset:480
	ds_read_b128 v[138:141], v78 offset:496
	ds_read2st64_b32 v[142:143], v79 offset1:1
	ds_read2st64_b32 v[144:145], v79 offset0:2 offset1:3
	ds_read2st64_b32 v[146:147], v79 offset0:4 offset1:5
	ds_read2st64_b32 v[148:149], v79 offset0:6 offset1:7
	ds_read2st64_b32 v[150:151], v79 offset0:8 offset1:9
	ds_read2st64_b32 v[152:153], v79 offset0:10 offset1:11
	ds_read2st64_b32 v[154:155], v79 offset0:12 offset1:13
	ds_read2st64_b32 v[156:157], v79 offset0:14 offset1:15
	ds_read2st64_b32 v[158:159], v79 offset0:16 offset1:17
	ds_read2st64_b32 v[160:161], v79 offset0:18 offset1:19
	ds_read2st64_b32 v[162:163], v79 offset0:20 offset1:21
	ds_read2st64_b32 v[164:165], v79 offset0:22 offset1:23
	ds_read2st64_b32 v[166:167], v79 offset0:24 offset1:25
	ds_read2st64_b32 v[168:169], v79 offset0:26 offset1:27
	ds_read2st64_b32 v[170:171], v79 offset0:28 offset1:29
	ds_read2st64_b32 v[172:173], v79 offset0:30 offset1:31
	v_mfma_f32_4x4x1_16b_f32 v[174:177], v6, v42, v[174:177]
	v_mfma_f32_4x4x1_16b_f32 v[178:181], v7, v43, v[178:181]
	v_mfma_f32_4x4x1_16b_f32 v[182:185], v8, v44, v[182:185]
	v_mfma_f32_4x4x1_16b_f32 v[186:189], v9, v45, v[186:189]
	v_mfma_f32_4x4x1_16b_f32 v[174:177], v10, v46, v[174:177]
	v_mfma_f32_4x4x1_16b_f32 v[178:181], v11, v47, v[178:181]
	v_mfma_f32_4x4x1_16b_f32 v[182:185], v12, v48, v[182:185]
	v_mfma_f32_4x4x1_16b_f32 v[186:189], v13, v49, v[186:189]
	v_mfma_f32_4x4x1_16b_f32 v[174:177], v14, v50, v[174:177]
	v_mfma_f32_4x4x1_16b_f32 v[178:181], v15, v51, v[178:181]
	v_mfma_f32_4x4x1_16b_f32 v[182:185], v16, v52, v[182:185]
	v_mfma_f32_4x4x1_16b_f32 v[186:189], v17, v53, v[186:189]
	v_mfma_f32_4x4x1_16b_f32 v[174:177], v18, v54, v[174:177]
	v_mfma_f32_4x4x1_16b_f32 v[178:181], v19, v55, v[178:181]
	v_mfma_f32_4x4x1_16b_f32 v[182:185], v20, v56, v[182:185]
	v_mfma_f32_4x4x1_16b_f32 v[186:189], v21, v57, v[186:189]
	v_mfma_f32_4x4x1_16b_f32 v[174:177], v22, v58, v[174:177]
	v_mfma_f32_4x4x1_16b_f32 v[178:181], v23, v59, v[178:181]
	v_mfma_f32_4x4x1_16b_f32 v[182:185], v24, v60, v[182:185]
	v_mfma_f32_4x4x1_16b_f32 v[186:189], v25, v61, v[186:189]
	v_mfma_f32_4x4x1_16b_f32 v[174:177], v26, v62, v[174:177]
	v_mfma_f32_4x4x1_16b_f32 v[178:181], v27, v63, v[178:181]
	v_mfma_f32_4x4x1_16b_f32 v[182:185], v28, v64, v[182:185]
	v_mfma_f32_4x4x1_16b_f32 v[186:189], v29, v65, v[186:189]
	v_mfma_f32_4x4x1_16b_f32 v[174:177], v30, v66, v[174:177]
	v_mfma_f32_4x4x1_16b_f32 v[178:181], v31, v67, v[178:181]
	v_mfma_f32_4x4x1_16b_f32 v[182:185], v32, v68, v[182:185]
	v_mfma_f32_4x4x1_16b_f32 v[186:189], v33, v69, v[186:189]
	v_mfma_f32_4x4x1_16b_f32 v[174:177], v34, v70, v[174:177]
	v_mfma_f32_4x4x1_16b_f32 v[178:181], v35, v71, v[178:181]
	v_mfma_f32_4x4x1_16b_f32 v[182:185], v36, v72, v[182:185]
	v_mfma_f32_4x4x1_16b_f32 v[186:189], v37, v73, v[186:189]
	s_waitcnt lgkmcnt(0)
	v_add_u32_e32 v79, 0x4000, v79
	ds_read_b128 v[6:9], v78 offset:512
	ds_read_b128 v[10:13], v78 offset:528
	ds_read_b128 v[14:17], v78 offset:544
	ds_read_b128 v[18:21], v78 offset:560
	ds_read_b128 v[22:25], v78 offset:576
	ds_read_b128 v[26:29], v78 offset:592
	ds_read_b128 v[30:33], v78 offset:608
	ds_read_b128 v[34:37], v78 offset:624
	ds_read2st64_b32 v[42:43], v79 offset1:1
	ds_read2st64_b32 v[44:45], v79 offset0:2 offset1:3
	ds_read2st64_b32 v[46:47], v79 offset0:4 offset1:5
	ds_read2st64_b32 v[48:49], v79 offset0:6 offset1:7
	ds_read2st64_b32 v[50:51], v79 offset0:8 offset1:9
	ds_read2st64_b32 v[52:53], v79 offset0:10 offset1:11
	ds_read2st64_b32 v[54:55], v79 offset0:12 offset1:13
	ds_read2st64_b32 v[56:57], v79 offset0:14 offset1:15
	ds_read2st64_b32 v[58:59], v79 offset0:16 offset1:17
	ds_read2st64_b32 v[60:61], v79 offset0:18 offset1:19
	ds_read2st64_b32 v[62:63], v79 offset0:20 offset1:21
	ds_read2st64_b32 v[64:65], v79 offset0:22 offset1:23
	ds_read2st64_b32 v[66:67], v79 offset0:24 offset1:25
	ds_read2st64_b32 v[68:69], v79 offset0:26 offset1:27
	ds_read2st64_b32 v[70:71], v79 offset0:28 offset1:29
	ds_read2st64_b32 v[72:73], v79 offset0:30 offset1:31
	v_mfma_f32_4x4x1_16b_f32 v[174:177], v110, v142, v[174:177]
	v_mfma_f32_4x4x1_16b_f32 v[178:181], v111, v143, v[178:181]
	v_mfma_f32_4x4x1_16b_f32 v[182:185], v112, v144, v[182:185]
	v_mfma_f32_4x4x1_16b_f32 v[186:189], v113, v145, v[186:189]
	v_mfma_f32_4x4x1_16b_f32 v[174:177], v114, v146, v[174:177]
	v_mfma_f32_4x4x1_16b_f32 v[178:181], v115, v147, v[178:181]
	v_mfma_f32_4x4x1_16b_f32 v[182:185], v116, v148, v[182:185]
	v_mfma_f32_4x4x1_16b_f32 v[186:189], v117, v149, v[186:189]
	v_mfma_f32_4x4x1_16b_f32 v[174:177], v118, v150, v[174:177]
	v_mfma_f32_4x4x1_16b_f32 v[178:181], v119, v151, v[178:181]
	v_mfma_f32_4x4x1_16b_f32 v[182:185], v120, v152, v[182:185]
	v_mfma_f32_4x4x1_16b_f32 v[186:189], v121, v153, v[186:189]
	v_mfma_f32_4x4x1_16b_f32 v[174:177], v122, v154, v[174:177]
	v_mfma_f32_4x4x1_16b_f32 v[178:181], v123, v155, v[178:181]
	v_mfma_f32_4x4x1_16b_f32 v[182:185], v124, v156, v[182:185]
	v_mfma_f32_4x4x1_16b_f32 v[186:189], v125, v157, v[186:189]
	v_mfma_f32_4x4x1_16b_f32 v[174:177], v126, v158, v[174:177]
	v_mfma_f32_4x4x1_16b_f32 v[178:181], v127, v159, v[178:181]
	v_mfma_f32_4x4x1_16b_f32 v[182:185], v128, v160, v[182:185]
	v_mfma_f32_4x4x1_16b_f32 v[186:189], v129, v161, v[186:189]
	v_mfma_f32_4x4x1_16b_f32 v[174:177], v130, v162, v[174:177]
	v_mfma_f32_4x4x1_16b_f32 v[178:181], v131, v163, v[178:181]
	v_mfma_f32_4x4x1_16b_f32 v[182:185], v132, v164, v[182:185]
	v_mfma_f32_4x4x1_16b_f32 v[186:189], v133, v165, v[186:189]
	v_mfma_f32_4x4x1_16b_f32 v[174:177], v134, v166, v[174:177]
	v_mfma_f32_4x4x1_16b_f32 v[178:181], v135, v167, v[178:181]
	v_mfma_f32_4x4x1_16b_f32 v[182:185], v136, v168, v[182:185]
	v_mfma_f32_4x4x1_16b_f32 v[186:189], v137, v169, v[186:189]
	v_mfma_f32_4x4x1_16b_f32 v[174:177], v138, v170, v[174:177]
	v_mfma_f32_4x4x1_16b_f32 v[178:181], v139, v171, v[178:181]
	v_mfma_f32_4x4x1_16b_f32 v[182:185], v140, v172, v[182:185]
	v_mfma_f32_4x4x1_16b_f32 v[186:189], v141, v173, v[186:189]
	s_waitcnt lgkmcnt(0)
	v_add_u32_e32 v79, 0x4000, v79
	ds_read_b128 v[110:113], v78 offset:640
	ds_read_b128 v[114:117], v78 offset:656
	ds_read_b128 v[118:121], v78 offset:672
	ds_read_b128 v[122:125], v78 offset:688
	ds_read_b128 v[126:129], v78 offset:704
	ds_read_b128 v[130:133], v78 offset:720
	ds_read_b128 v[134:137], v78 offset:736
	ds_read_b128 v[138:141], v78 offset:752
	ds_read2st64_b32 v[142:143], v79 offset1:1
	ds_read2st64_b32 v[144:145], v79 offset0:2 offset1:3
	ds_read2st64_b32 v[146:147], v79 offset0:4 offset1:5
	ds_read2st64_b32 v[148:149], v79 offset0:6 offset1:7
	ds_read2st64_b32 v[150:151], v79 offset0:8 offset1:9
	ds_read2st64_b32 v[152:153], v79 offset0:10 offset1:11
	ds_read2st64_b32 v[154:155], v79 offset0:12 offset1:13
	ds_read2st64_b32 v[156:157], v79 offset0:14 offset1:15
	ds_read2st64_b32 v[158:159], v79 offset0:16 offset1:17
	ds_read2st64_b32 v[160:161], v79 offset0:18 offset1:19
	ds_read2st64_b32 v[162:163], v79 offset0:20 offset1:21
	ds_read2st64_b32 v[164:165], v79 offset0:22 offset1:23
	ds_read2st64_b32 v[166:167], v79 offset0:24 offset1:25
	ds_read2st64_b32 v[168:169], v79 offset0:26 offset1:27
	ds_read2st64_b32 v[170:171], v79 offset0:28 offset1:29
	ds_read2st64_b32 v[172:173], v79 offset0:30 offset1:31
	v_mfma_f32_4x4x1_16b_f32 v[174:177], v6, v42, v[174:177]
	v_mfma_f32_4x4x1_16b_f32 v[178:181], v7, v43, v[178:181]
	v_mfma_f32_4x4x1_16b_f32 v[182:185], v8, v44, v[182:185]
	v_mfma_f32_4x4x1_16b_f32 v[186:189], v9, v45, v[186:189]
	v_mfma_f32_4x4x1_16b_f32 v[174:177], v10, v46, v[174:177]
	v_mfma_f32_4x4x1_16b_f32 v[178:181], v11, v47, v[178:181]
	v_mfma_f32_4x4x1_16b_f32 v[182:185], v12, v48, v[182:185]
	v_mfma_f32_4x4x1_16b_f32 v[186:189], v13, v49, v[186:189]
	v_mfma_f32_4x4x1_16b_f32 v[174:177], v14, v50, v[174:177]
	v_mfma_f32_4x4x1_16b_f32 v[178:181], v15, v51, v[178:181]
	v_mfma_f32_4x4x1_16b_f32 v[182:185], v16, v52, v[182:185]
	v_mfma_f32_4x4x1_16b_f32 v[186:189], v17, v53, v[186:189]
	v_mfma_f32_4x4x1_16b_f32 v[174:177], v18, v54, v[174:177]
	v_mfma_f32_4x4x1_16b_f32 v[178:181], v19, v55, v[178:181]
	v_mfma_f32_4x4x1_16b_f32 v[182:185], v20, v56, v[182:185]
	v_mfma_f32_4x4x1_16b_f32 v[186:189], v21, v57, v[186:189]
	v_mfma_f32_4x4x1_16b_f32 v[174:177], v22, v58, v[174:177]
	v_mfma_f32_4x4x1_16b_f32 v[178:181], v23, v59, v[178:181]
	v_mfma_f32_4x4x1_16b_f32 v[182:185], v24, v60, v[182:185]
	v_mfma_f32_4x4x1_16b_f32 v[186:189], v25, v61, v[186:189]
	v_mfma_f32_4x4x1_16b_f32 v[174:177], v26, v62, v[174:177]
	v_mfma_f32_4x4x1_16b_f32 v[178:181], v27, v63, v[178:181]
	v_mfma_f32_4x4x1_16b_f32 v[182:185], v28, v64, v[182:185]
	v_mfma_f32_4x4x1_16b_f32 v[186:189], v29, v65, v[186:189]
	v_mfma_f32_4x4x1_16b_f32 v[174:177], v30, v66, v[174:177]
	v_mfma_f32_4x4x1_16b_f32 v[178:181], v31, v67, v[178:181]
	v_mfma_f32_4x4x1_16b_f32 v[182:185], v32, v68, v[182:185]
	v_mfma_f32_4x4x1_16b_f32 v[186:189], v33, v69, v[186:189]
	v_mfma_f32_4x4x1_16b_f32 v[174:177], v34, v70, v[174:177]
	v_mfma_f32_4x4x1_16b_f32 v[178:181], v35, v71, v[178:181]
	v_mfma_f32_4x4x1_16b_f32 v[182:185], v36, v72, v[182:185]
	v_mfma_f32_4x4x1_16b_f32 v[186:189], v37, v73, v[186:189]
	s_waitcnt lgkmcnt(0)
	v_add_u32_e32 v79, 0x4000, v79
	ds_read_b128 v[6:9], v78 offset:768
	ds_read_b128 v[10:13], v78 offset:784
	ds_read_b128 v[14:17], v78 offset:800
	ds_read_b128 v[18:21], v78 offset:816
	ds_read_b128 v[22:25], v78 offset:832
	ds_read_b128 v[26:29], v78 offset:848
	ds_read_b128 v[30:33], v78 offset:864
	ds_read_b128 v[34:37], v78 offset:880
	ds_read2st64_b32 v[42:43], v79 offset1:1
	ds_read2st64_b32 v[44:45], v79 offset0:2 offset1:3
	ds_read2st64_b32 v[46:47], v79 offset0:4 offset1:5
	ds_read2st64_b32 v[48:49], v79 offset0:6 offset1:7
	ds_read2st64_b32 v[50:51], v79 offset0:8 offset1:9
	ds_read2st64_b32 v[52:53], v79 offset0:10 offset1:11
	ds_read2st64_b32 v[54:55], v79 offset0:12 offset1:13
	ds_read2st64_b32 v[56:57], v79 offset0:14 offset1:15
	ds_read2st64_b32 v[58:59], v79 offset0:16 offset1:17
	ds_read2st64_b32 v[60:61], v79 offset0:18 offset1:19
	ds_read2st64_b32 v[62:63], v79 offset0:20 offset1:21
	ds_read2st64_b32 v[64:65], v79 offset0:22 offset1:23
	ds_read2st64_b32 v[66:67], v79 offset0:24 offset1:25
	ds_read2st64_b32 v[68:69], v79 offset0:26 offset1:27
	ds_read2st64_b32 v[70:71], v79 offset0:28 offset1:29
	ds_read2st64_b32 v[72:73], v79 offset0:30 offset1:31
	v_mfma_f32_4x4x1_16b_f32 v[174:177], v110, v142, v[174:177]
	v_mfma_f32_4x4x1_16b_f32 v[178:181], v111, v143, v[178:181]
	v_mfma_f32_4x4x1_16b_f32 v[182:185], v112, v144, v[182:185]
	v_mfma_f32_4x4x1_16b_f32 v[186:189], v113, v145, v[186:189]
	v_mfma_f32_4x4x1_16b_f32 v[174:177], v114, v146, v[174:177]
	v_mfma_f32_4x4x1_16b_f32 v[178:181], v115, v147, v[178:181]
	v_mfma_f32_4x4x1_16b_f32 v[182:185], v116, v148, v[182:185]
	v_mfma_f32_4x4x1_16b_f32 v[186:189], v117, v149, v[186:189]
	v_mfma_f32_4x4x1_16b_f32 v[174:177], v118, v150, v[174:177]
	v_mfma_f32_4x4x1_16b_f32 v[178:181], v119, v151, v[178:181]
	v_mfma_f32_4x4x1_16b_f32 v[182:185], v120, v152, v[182:185]
	v_mfma_f32_4x4x1_16b_f32 v[186:189], v121, v153, v[186:189]
	v_mfma_f32_4x4x1_16b_f32 v[174:177], v122, v154, v[174:177]
	v_mfma_f32_4x4x1_16b_f32 v[178:181], v123, v155, v[178:181]
	v_mfma_f32_4x4x1_16b_f32 v[182:185], v124, v156, v[182:185]
	v_mfma_f32_4x4x1_16b_f32 v[186:189], v125, v157, v[186:189]
	v_mfma_f32_4x4x1_16b_f32 v[174:177], v126, v158, v[174:177]
	v_mfma_f32_4x4x1_16b_f32 v[178:181], v127, v159, v[178:181]
	v_mfma_f32_4x4x1_16b_f32 v[182:185], v128, v160, v[182:185]
	v_mfma_f32_4x4x1_16b_f32 v[186:189], v129, v161, v[186:189]
	v_mfma_f32_4x4x1_16b_f32 v[174:177], v130, v162, v[174:177]
	v_mfma_f32_4x4x1_16b_f32 v[178:181], v131, v163, v[178:181]
	v_mfma_f32_4x4x1_16b_f32 v[182:185], v132, v164, v[182:185]
	v_mfma_f32_4x4x1_16b_f32 v[186:189], v133, v165, v[186:189]
	v_mfma_f32_4x4x1_16b_f32 v[174:177], v134, v166, v[174:177]
	v_mfma_f32_4x4x1_16b_f32 v[178:181], v135, v167, v[178:181]
	v_mfma_f32_4x4x1_16b_f32 v[182:185], v136, v168, v[182:185]
	v_mfma_f32_4x4x1_16b_f32 v[186:189], v137, v169, v[186:189]
	v_mfma_f32_4x4x1_16b_f32 v[174:177], v138, v170, v[174:177]
	v_mfma_f32_4x4x1_16b_f32 v[178:181], v139, v171, v[178:181]
	v_mfma_f32_4x4x1_16b_f32 v[182:185], v140, v172, v[182:185]
	v_mfma_f32_4x4x1_16b_f32 v[186:189], v141, v173, v[186:189]
	s_waitcnt lgkmcnt(0)
	v_add_u32_e32 v79, 0x4000, v79
	ds_read_b128 v[110:113], v78 offset:896
	ds_read_b128 v[114:117], v78 offset:912
	ds_read_b128 v[118:121], v78 offset:928
	ds_read_b128 v[122:125], v78 offset:944
	ds_read_b128 v[126:129], v78 offset:960
	ds_read_b128 v[130:133], v78 offset:976
	ds_read_b128 v[134:137], v78 offset:992
	ds_read_b128 v[138:141], v78 offset:1008
	ds_read2st64_b32 v[142:143], v79 offset1:1
	ds_read2st64_b32 v[144:145], v79 offset0:2 offset1:3
	ds_read2st64_b32 v[146:147], v79 offset0:4 offset1:5
	ds_read2st64_b32 v[148:149], v79 offset0:6 offset1:7
	ds_read2st64_b32 v[150:151], v79 offset0:8 offset1:9
	ds_read2st64_b32 v[152:153], v79 offset0:10 offset1:11
	ds_read2st64_b32 v[154:155], v79 offset0:12 offset1:13
	ds_read2st64_b32 v[156:157], v79 offset0:14 offset1:15
	ds_read2st64_b32 v[158:159], v79 offset0:16 offset1:17
	ds_read2st64_b32 v[160:161], v79 offset0:18 offset1:19
	ds_read2st64_b32 v[162:163], v79 offset0:20 offset1:21
	ds_read2st64_b32 v[164:165], v79 offset0:22 offset1:23
	ds_read2st64_b32 v[166:167], v79 offset0:24 offset1:25
	ds_read2st64_b32 v[168:169], v79 offset0:26 offset1:27
	ds_read2st64_b32 v[170:171], v79 offset0:28 offset1:29
	ds_read2st64_b32 v[172:173], v79 offset0:30 offset1:31
	v_mfma_f32_4x4x1_16b_f32 v[174:177], v6, v42, v[174:177]
	v_mfma_f32_4x4x1_16b_f32 v[178:181], v7, v43, v[178:181]
	v_mfma_f32_4x4x1_16b_f32 v[182:185], v8, v44, v[182:185]
	v_mfma_f32_4x4x1_16b_f32 v[186:189], v9, v45, v[186:189]
	v_mfma_f32_4x4x1_16b_f32 v[174:177], v10, v46, v[174:177]
	v_mfma_f32_4x4x1_16b_f32 v[178:181], v11, v47, v[178:181]
	v_mfma_f32_4x4x1_16b_f32 v[182:185], v12, v48, v[182:185]
	v_mfma_f32_4x4x1_16b_f32 v[186:189], v13, v49, v[186:189]
	v_mfma_f32_4x4x1_16b_f32 v[174:177], v14, v50, v[174:177]
	v_mfma_f32_4x4x1_16b_f32 v[178:181], v15, v51, v[178:181]
	v_mfma_f32_4x4x1_16b_f32 v[182:185], v16, v52, v[182:185]
	v_mfma_f32_4x4x1_16b_f32 v[186:189], v17, v53, v[186:189]
	v_mfma_f32_4x4x1_16b_f32 v[174:177], v18, v54, v[174:177]
	v_mfma_f32_4x4x1_16b_f32 v[178:181], v19, v55, v[178:181]
	v_mfma_f32_4x4x1_16b_f32 v[182:185], v20, v56, v[182:185]
	v_mfma_f32_4x4x1_16b_f32 v[186:189], v21, v57, v[186:189]
	v_mfma_f32_4x4x1_16b_f32 v[174:177], v22, v58, v[174:177]
	v_mfma_f32_4x4x1_16b_f32 v[178:181], v23, v59, v[178:181]
	v_mfma_f32_4x4x1_16b_f32 v[182:185], v24, v60, v[182:185]
	v_mfma_f32_4x4x1_16b_f32 v[186:189], v25, v61, v[186:189]
	v_mfma_f32_4x4x1_16b_f32 v[174:177], v26, v62, v[174:177]
	v_mfma_f32_4x4x1_16b_f32 v[178:181], v27, v63, v[178:181]
	v_mfma_f32_4x4x1_16b_f32 v[182:185], v28, v64, v[182:185]
	v_mfma_f32_4x4x1_16b_f32 v[186:189], v29, v65, v[186:189]
	v_mfma_f32_4x4x1_16b_f32 v[174:177], v30, v66, v[174:177]
	v_mfma_f32_4x4x1_16b_f32 v[178:181], v31, v67, v[178:181]
	v_mfma_f32_4x4x1_16b_f32 v[182:185], v32, v68, v[182:185]
	v_mfma_f32_4x4x1_16b_f32 v[186:189], v33, v69, v[186:189]
	v_mfma_f32_4x4x1_16b_f32 v[174:177], v34, v70, v[174:177]
	v_mfma_f32_4x4x1_16b_f32 v[178:181], v35, v71, v[178:181]
	v_mfma_f32_4x4x1_16b_f32 v[182:185], v36, v72, v[182:185]
	v_mfma_f32_4x4x1_16b_f32 v[186:189], v37, v73, v[186:189]
	s_waitcnt lgkmcnt(0)
	v_mfma_f32_4x4x1_16b_f32 v[174:177], v110, v142, v[174:177]
	v_mfma_f32_4x4x1_16b_f32 v[178:181], v111, v143, v[178:181]
	v_mfma_f32_4x4x1_16b_f32 v[182:185], v112, v144, v[182:185]
	v_mfma_f32_4x4x1_16b_f32 v[186:189], v113, v145, v[186:189]
	v_mfma_f32_4x4x1_16b_f32 v[174:177], v114, v146, v[174:177]
	v_mfma_f32_4x4x1_16b_f32 v[178:181], v115, v147, v[178:181]
	v_mfma_f32_4x4x1_16b_f32 v[182:185], v116, v148, v[182:185]
	v_mfma_f32_4x4x1_16b_f32 v[186:189], v117, v149, v[186:189]
	v_mfma_f32_4x4x1_16b_f32 v[174:177], v118, v150, v[174:177]
	v_mfma_f32_4x4x1_16b_f32 v[178:181], v119, v151, v[178:181]
	v_mfma_f32_4x4x1_16b_f32 v[182:185], v120, v152, v[182:185]
	v_mfma_f32_4x4x1_16b_f32 v[186:189], v121, v153, v[186:189]
	v_mfma_f32_4x4x1_16b_f32 v[174:177], v122, v154, v[174:177]
	v_mfma_f32_4x4x1_16b_f32 v[178:181], v123, v155, v[178:181]
	v_mfma_f32_4x4x1_16b_f32 v[182:185], v124, v156, v[182:185]
	v_mfma_f32_4x4x1_16b_f32 v[186:189], v125, v157, v[186:189]
	v_mfma_f32_4x4x1_16b_f32 v[174:177], v126, v158, v[174:177]
	v_mfma_f32_4x4x1_16b_f32 v[178:181], v127, v159, v[178:181]
	v_mfma_f32_4x4x1_16b_f32 v[182:185], v128, v160, v[182:185]
	v_mfma_f32_4x4x1_16b_f32 v[186:189], v129, v161, v[186:189]
	v_mfma_f32_4x4x1_16b_f32 v[174:177], v130, v162, v[174:177]
	v_mfma_f32_4x4x1_16b_f32 v[178:181], v131, v163, v[178:181]
	v_mfma_f32_4x4x1_16b_f32 v[182:185], v132, v164, v[182:185]
	v_mfma_f32_4x4x1_16b_f32 v[186:189], v133, v165, v[186:189]
	v_mfma_f32_4x4x1_16b_f32 v[174:177], v134, v166, v[174:177]
	v_mfma_f32_4x4x1_16b_f32 v[178:181], v135, v167, v[178:181]
	v_mfma_f32_4x4x1_16b_f32 v[182:185], v136, v168, v[182:185]
	v_mfma_f32_4x4x1_16b_f32 v[186:189], v137, v169, v[186:189]
	v_mfma_f32_4x4x1_16b_f32 v[174:177], v138, v170, v[174:177]
	v_mfma_f32_4x4x1_16b_f32 v[178:181], v139, v171, v[178:181]
	v_mfma_f32_4x4x1_16b_f32 v[182:185], v140, v172, v[182:185]
	v_mfma_f32_4x4x1_16b_f32 v[186:189], v141, v173, v[186:189]
	s_nop 4
	v_add_f32_e32 v174, v174, v178
	v_add_f32_e32 v182, v182, v186
	v_add_f32_e32 v175, v175, v179
	v_add_f32_e32 v183, v183, v187
	v_add_f32_e32 v176, v176, v180
	v_add_f32_e32 v184, v184, v188
	v_add_f32_e32 v177, v177, v181
	v_add_f32_e32 v185, v185, v189
	v_add_f32_e32 v4, v174, v182
	v_add_f32_e32 v5, v175, v183
	v_add_f32_e32 v2, v176, v184
	v_add_f32_e32 v3, v177, v185
	s_ashr_i32 s11, s10, 31
	s_lshl_b64 s[4:5], s[10:11], 19
	s_add_u32 s4, s6, s4
	s_addc_u32 s5, s7, s5
	v_mov_b32_e32 v39, 0
	v_lshl_add_u64 v[6:7], s[4:5], 0, v[38:39]
	s_mov_b64 s[4:5], 0x5c00000
	v_lshl_add_u64 v[6:7], v[6:7], 0, s[4:5]
	s_lshr_b32 s4, s22, 1
	s_lshr_b32 s5, s23, 4
	s_and_b32 s17, s4, 4
	s_add_u32 s10, s6, 0x7e80000
	v_and_b32_e32 v8, 31, v1
	s_addc_u32 s11, s7, 0
	v_lshrrev_b32_e32 v9, 3, v1
	s_lshl_b32 s3, s3, 5
	v_and_b32_e32 v1, 7, v1
	v_and_or_b32 v14, s3, 32, v8
	v_lshlrev_b32_e32 v38, 1, v1
	v_bfe_u32 v1, v4, 16, 1
	s_movk_i32 s3, 0x7fff
	s_mov_b32 s13, 0
	v_and_b32_e32 v9, 4, v9
	v_add3_u32 v1, v4, v1, s3
	s_lshl_b32 s12, s16, 7
	s_lshr_b32 s4, s23, 3
	v_and_or_b32 v12, s5, 3, v9
	v_lshrrev_b32_e32 v13, 16, v1
	v_lshl_add_u64 v[8:9], v[6:7], 0, s[12:13]
	s_and_b32 s18, s4, 0x1c0
	v_lshl_add_u64 v[10:11], s[6:7], 0, v[38:39]
	s_mov_b64 s[6:7], 0x7e00000
	global_store_short v[8:9], v13, off
	s_bfe_u32 s19, s23, 0x30006
	s_mov_b64 s[14:15], -1
	s_and_b64 vcc, exec, s[8:9]
	v_lshlrev_b32_e32 v8, 4, v14
	s_cbranch_vccz .LBB0_1175
	s_lshl_b32 s3, s19, 3
	s_or_b32 s3, s3, s18
	v_or_b32_e32 v1, s3, v12
	v_lshlrev_b32_e32 v38, 10, v1
	v_mov_b32_e32 v9, v39
	v_lshl_add_u64 v[14:15], s[10:11], 0, v[38:39]
	v_lshl_add_u64 v[14:15], v[14:15], 0, v[8:9]
	s_lshl_b32 s12, s17, 1
	v_lshl_add_u64 v[14:15], v[14:15], 0, s[12:13]
	global_store_short v[14:15], v13, off
	s_mov_b64 s[14:15], 0
